# remaining interleaved IEEE f32 division expansions (LRU gate epilogue etc.) -> v_rcp_f32
# speedup vs baseline: 1.0263x; 1.0157x over previous
.LBB0_191:
	s_waitcnt lgkmcnt(0)
	v_lshl_add_u64 v[34:35], s[26:27], 0, v[8:9]
	v_add_co_u32_e32 v14, vcc, 0x15205000, v34
	v_lshl_add_u64 v[12:13], s[26:27], 0, v[6:7]
	s_nop 0
	v_addc_co_u32_e32 v15, vcc, 0, v35, vcc
	v_add_co_u32_e32 v16, vcc, 0x17245000, v34
	global_load_dword v24, v[14:15], off
	s_nop 0
	v_addc_co_u32_e32 v17, vcc, 0, v35, vcc
	global_load_dword v38, v[16:17], off
	global_load_dword v39, v[14:15], off offset:2048
	global_load_dword v40, v[16:17], off offset:2048
	v_add_co_u32_e32 v14, vcc, 0x15206000, v34
	s_mov_b32 s17, 0x35a5000
	s_nop 0
	v_addc_co_u32_e32 v15, vcc, 0, v35, vcc
	v_add_co_u32_e32 v16, vcc, 0x17246000, v34
	global_load_dword v41, v[14:15], off
	s_nop 0
	v_addc_co_u32_e32 v17, vcc, 0, v35, vcc
	global_load_dword v42, v[16:17], off
	global_load_dword v43, v[14:15], off offset:2048
	global_load_dword v44, v[16:17], off offset:2048
	v_add_co_u32_e32 v14, vcc, 0x15207000, v34
	v_lshl_add_u64 v[8:9], v[8:9], 0, s[24:25]
	s_nop 0
	v_addc_co_u32_e32 v15, vcc, 0, v35, vcc
	v_add_co_u32_e32 v16, vcc, 0x17247000, v34
	global_load_dword v45, v[14:15], off
	s_nop 0
	v_addc_co_u32_e32 v17, vcc, 0, v35, vcc
	global_load_dword v46, v[16:17], off
	global_load_dword v47, v[14:15], off offset:2048
	global_load_dword v48, v[16:17], off offset:2048
	v_add_co_u32_e32 v14, vcc, 0x15208000, v34
	s_waitcnt vmcnt(10)
	v_fmac_f32_e32 v38, v11, v24
	v_addc_co_u32_e32 v15, vcc, 0, v35, vcc
	v_add_co_u32_e32 v16, vcc, 0x17248000, v34
	global_load_dword v49, v[14:15], off
	s_nop 0
	v_addc_co_u32_e32 v17, vcc, 0, v35, vcc
	global_load_dword v31, v[16:17], off
	global_load_dword v32, v[14:15], off offset:2048
	global_load_dword v27, v[16:17], off offset:2048
	v_add_co_u32_e32 v14, vcc, 0x15209000, v34
	s_waitcnt vmcnt(12)
	v_fmac_f32_e32 v40, v38, v39
	v_addc_co_u32_e32 v15, vcc, 0, v35, vcc
	v_add_co_u32_e32 v16, vcc, 0x17249000, v34
	global_load_dword v28, v[14:15], off
	s_nop 0
	v_addc_co_u32_e32 v17, vcc, 0, v35, vcc
	global_load_dword v25, v[16:17], off
	global_load_dword v26, v[14:15], off offset:2048
	global_load_dword v22, v[16:17], off offset:2048
	v_add_co_u32_e32 v14, vcc, 0x1520a000, v34
	s_waitcnt vmcnt(14)
	v_fmac_f32_e32 v42, v40, v41
	v_addc_co_u32_e32 v15, vcc, 0, v35, vcc
	v_add_co_u32_e32 v16, vcc, 0x1724a000, v34
	global_load_dword v23, v[14:15], off
	s_nop 0
	v_addc_co_u32_e32 v17, vcc, 0, v35, vcc
	global_load_dword v20, v[16:17], off
	global_load_dword v21, v[14:15], off offset:2048
	global_load_dword v18, v[16:17], off offset:2048
	v_add_co_u32_e32 v14, vcc, 0x1520b000, v34
	s_waitcnt vmcnt(16)
	v_fmac_f32_e32 v44, v42, v43
	v_addc_co_u32_e32 v15, vcc, 0, v35, vcc
	v_add_co_u32_e32 v36, vcc, 0x1724b000, v34
	global_load_dword v19, v[14:15], off
	s_nop 0
	v_addc_co_u32_e32 v37, vcc, 0, v35, vcc
	global_load_dword v16, v[36:37], off
	global_load_dword v17, v[14:15], off offset:2048
	s_nop 0
	global_load_dword v14, v[36:37], off offset:2048
	v_add_co_u32_e32 v36, vcc, 0x1520c000, v34
	s_waitcnt vmcnt(18)
	v_fmac_f32_e32 v46, v44, v45
	v_addc_co_u32_e32 v37, vcc, 0, v35, vcc
	v_add_co_u32_e32 v34, vcc, 0x1724c000, v34
	global_load_dword v15, v[36:37], off
	s_nop 0
	v_addc_co_u32_e32 v35, vcc, 0, v35, vcc
	global_load_dword v0, v[34:35], off
	global_load_dword v3, v[36:37], off offset:2048
	global_load_dword v10, v[34:35], off offset:2048
	v_add_co_u32_e32 v34, vcc, 0x35a6000, v12
	s_waitcnt vmcnt(20)
	v_fmac_f32_e32 v48, v46, v47
	v_addc_co_u32_e32 v35, vcc, 0, v13, vcc
	global_load_ushort v11, v[34:35], off offset:3072
	s_waitcnt vmcnt(19)
	v_fmac_f32_e32 v31, v48, v49
	s_waitcnt vmcnt(17)
	v_fmac_f32_e32 v27, v31, v32
	s_waitcnt vmcnt(15)
	v_fmac_f32_e32 v25, v27, v28
	s_waitcnt vmcnt(13)
	v_fmac_f32_e32 v22, v25, v26
	s_waitcnt vmcnt(11)
	v_fmac_f32_e32 v20, v22, v23
	s_waitcnt vmcnt(9)
	v_fmac_f32_e32 v18, v20, v21
	s_waitcnt vmcnt(7)
	v_fmac_f32_e32 v16, v18, v19
	s_waitcnt vmcnt(5)
	v_fmac_f32_e32 v14, v16, v17
	s_waitcnt vmcnt(3)
	v_fmac_f32_e32 v0, v14, v15
	s_waitcnt vmcnt(0)
	v_lshlrev_b32_e32 v11, 16, v11
	v_mul_f32_e32 v24, 0xbfb8aa3b, v11
	v_exp_f32_e32 v24, v24
	s_nop 0
	v_add_f32_e32 v24, 1.0, v24
	v_div_scale_f32 v29, s[18:19], v24, v24, v11
	v_rcp_f32_e32 v33, v29
	s_nop 0
	v_fma_f32 v34, -v29, v33, 1.0
	v_fmac_f32_e32 v33, v34, v33
	v_div_scale_f32 v34, vcc, v11, v24, v11
	v_mul_f32_e32 v35, v34, v33
	v_fma_f32 v36, -v29, v35, v34
	v_fmac_f32_e32 v35, v36, v33
	v_fma_f32 v29, -v29, v35, v34
	v_div_fmas_f32 v29, v29, v33, v35
	v_add_co_u32_e32 v34, vcc, s17, v12
	s_mov_b32 s17, 0x35aa000
	s_nop 0
	v_addc_co_u32_e32 v35, vcc, 0, v13, vcc
	v_add_co_u32_e32 v36, vcc, s17, v12
	s_mov_b32 s17, 0x35ad000
	s_nop 0
	v_addc_co_u32_e32 v37, vcc, 0, v13, vcc
	global_load_ushort v51, v[36:37], off offset:1024
	v_add_co_u32_e32 v36, vcc, s17, v12
	s_mov_b32 s17, 0x35b1000
	s_nop 0
	v_addc_co_u32_e32 v37, vcc, 0, v13, vcc
	global_load_ushort v52, v[36:37], off offset:3072
	v_add_co_u32_e32 v36, vcc, s17, v12
	s_mov_b32 s17, 0x35b4000
	s_nop 0
	v_addc_co_u32_e32 v37, vcc, 0, v13, vcc
	global_load_ushort v53, v[36:37], off offset:1024
	v_add_co_u32_e32 v36, vcc, s17, v12
	s_mov_b32 s17, 0x35b8000
	s_nop 0
	v_addc_co_u32_e32 v37, vcc, 0, v13, vcc
	global_load_ushort v54, v[36:37], off offset:3072
	v_add_co_u32_e32 v36, vcc, s17, v12
	s_mov_b32 s17, 0x35bb000
	s_nop 0
	v_addc_co_u32_e32 v37, vcc, 0, v13, vcc
	global_load_ushort v55, v[36:37], off offset:1024
	v_add_co_u32_e32 v36, vcc, s17, v12
	s_mov_b32 s17, 0x35bf000
	s_nop 0
	v_addc_co_u32_e32 v37, vcc, 0, v13, vcc
	global_load_ushort v56, v[36:37], off offset:3072
	v_add_co_u32_e32 v36, vcc, s17, v12
	s_mov_b32 s17, 0x35c2000
	s_nop 0
	v_addc_co_u32_e32 v37, vcc, 0, v13, vcc
	global_load_ushort v57, v[36:37], off offset:1024
	v_add_co_u32_e32 v36, vcc, s17, v12
	s_mov_b32 s17, 0x35c6000
	s_nop 0
	v_addc_co_u32_e32 v37, vcc, 0, v13, vcc
	global_load_ushort v58, v[36:37], off offset:3072
	v_add_co_u32_e32 v36, vcc, s17, v12
	s_mov_b32 s17, 0x35c9000
	s_nop 0
	v_addc_co_u32_e32 v37, vcc, 0, v13, vcc
	global_load_ushort v59, v[36:37], off offset:1024
	v_add_co_u32_e32 v36, vcc, s17, v12
	s_mov_b32 s17, 0x35cd000
	s_nop 0
	v_addc_co_u32_e32 v37, vcc, 0, v13, vcc
	v_div_fixup_f32 v11, v29, v24, v11
	global_load_ushort v60, v[36:37], off offset:3072
	v_add_co_u32_e32 v36, vcc, s17, v12
	v_mul_f32_e32 v11, v38, v11
	s_nop 0
	v_addc_co_u32_e32 v37, vcc, 0, v13, vcc
	s_mov_b32 s17, 0x35d0000
	v_cvt_pk_bf16_f32 v50, v11, s0
	global_load_ushort v61, v[36:37], off offset:1024
	v_add_co_u32_e32 v36, vcc, s17, v12
	s_mov_b32 s17, 0x35d4000
	s_nop 0
	v_addc_co_u32_e32 v37, vcc, 0, v13, vcc
	global_store_short v[34:35], v50, off offset:3072
	global_load_ushort v33, v[36:37], off offset:3072
	v_add_co_u32_e32 v36, vcc, s17, v12
	s_mov_b32 s17, 0x35d7000
	s_nop 0
	v_addc_co_u32_e32 v37, vcc, 0, v13, vcc
	global_load_ushort v29, v[36:37], off offset:1024
	v_add_co_u32_e32 v36, vcc, s17, v12
	s_mov_b32 s17, 0x35db000
	s_waitcnt vmcnt(13)
	v_lshlrev_b32_e32 v34, 16, v51
	v_mul_f32_e32 v35, 0xbfb8aa3b, v34
	v_exp_f32_e32 v35, v35
	v_addc_co_u32_e32 v37, vcc, 0, v13, vcc
	global_load_ushort v11, v[36:37], off offset:3072
	v_add_co_u32_e32 v36, vcc, s17, v12
	v_add_f32_e32 v35, 1.0, v35
	s_nop 0
	v_addc_co_u32_e32 v37, vcc, 0, v13, vcc
	global_load_ushort v24, v[36:37], off offset:1024
	s_mov_b32 s17, 0x35a9000
	v_rcp_f32_e32 v37, v35
	s_nop 0
	v_mul_f32_e32 v34, v34, v37
	v_mul_f32_e32 v34, v40, v34
	v_cvt_pk_bf16_f32 v36, v34, s0
	v_add_co_u32_e32 v34, vcc, s17, v12
	s_mov_b32 s17, 0x35ac000
	s_nop 0
	v_addc_co_u32_e32 v35, vcc, 0, v13, vcc
	global_store_short v[34:35], v36, off offset:1024
	s_waitcnt vmcnt(15)
	v_lshlrev_b32_e32 v34, 16, v52
	v_mul_f32_e32 v35, 0xbfb8aa3b, v34
	v_exp_f32_e32 v35, v35
	s_waitcnt vmcnt(2)
	v_lshlrev_b32_e32 v11, 16, v11
	v_add_f32_e32 v35, 1.0, v35
	v_rcp_f32_e32 v37, v35
	s_nop 0
	v_mul_f32_e32 v34, v34, v37
	v_mul_f32_e32 v34, v42, v34
	v_cvt_pk_bf16_f32 v36, v34, s0
	v_add_co_u32_e32 v34, vcc, s17, v12
	s_mov_b32 s17, 0x35b0000
	s_nop 0
	v_addc_co_u32_e32 v35, vcc, 0, v13, vcc
	global_store_short v[34:35], v36, off offset:3072
	v_lshlrev_b32_e32 v34, 16, v53
	v_mul_f32_e32 v35, 0xbfb8aa3b, v34
	v_exp_f32_e32 v35, v35
	s_nop 0
	v_add_f32_e32 v35, 1.0, v35
	v_rcp_f32_e32 v37, v35
	s_nop 0
	v_mul_f32_e32 v34, v34, v37
	v_mul_f32_e32 v34, v44, v34
	v_cvt_pk_bf16_f32 v36, v34, s0
	v_add_co_u32_e32 v34, vcc, s17, v12
	s_mov_b32 s17, 0x35b3000
	s_nop 0
	v_addc_co_u32_e32 v35, vcc, 0, v13, vcc
	global_store_short v[34:35], v36, off offset:1024
	v_lshlrev_b32_e32 v34, 16, v54
	v_mul_f32_e32 v35, 0xbfb8aa3b, v34
	v_exp_f32_e32 v35, v35
	s_nop 0
	v_add_f32_e32 v35, 1.0, v35
	v_rcp_f32_e32 v37, v35
	s_nop 0
	v_mul_f32_e32 v34, v34, v37
	v_mul_f32_e32 v34, v46, v34
	v_cvt_pk_bf16_f32 v36, v34, s0
	v_add_co_u32_e32 v34, vcc, s17, v12
	s_mov_b32 s17, 0x35b7000
	s_nop 0
	v_addc_co_u32_e32 v35, vcc, 0, v13, vcc
	global_store_short v[34:35], v36, off offset:3072
	v_lshlrev_b32_e32 v34, 16, v55
	v_mul_f32_e32 v35, 0xbfb8aa3b, v34
	v_exp_f32_e32 v35, v35
	s_nop 0
	v_add_f32_e32 v35, 1.0, v35
	v_rcp_f32_e32 v37, v35
	s_nop 0
	v_mul_f32_e32 v34, v34, v37
	v_mul_f32_e32 v34, v48, v34
	v_cvt_pk_bf16_f32 v36, v34, s0
	v_add_co_u32_e32 v34, vcc, s17, v12
	s_mov_b32 s17, 0x35ba000
	s_nop 0
	v_addc_co_u32_e32 v35, vcc, 0, v13, vcc
	global_store_short v[34:35], v36, off offset:1024
	v_lshlrev_b32_e32 v34, 16, v56
	v_mul_f32_e32 v35, 0xbfb8aa3b, v34
	v_exp_f32_e32 v35, v35
	s_nop 0
	v_add_f32_e32 v35, 1.0, v35
	v_rcp_f32_e32 v37, v35
	s_nop 0
	v_mul_f32_e32 v34, v34, v37
	v_mul_f32_e32 v34, v31, v34
	v_lshlrev_b32_e32 v31, 16, v57
	v_mul_f32_e32 v32, 0xbfb8aa3b, v31
	v_exp_f32_e32 v32, v32
	v_cvt_pk_bf16_f32 v36, v34, s0
	v_add_co_u32_e32 v34, vcc, s17, v12
	v_add_f32_e32 v32, 1.0, v32
	s_nop 0
	v_addc_co_u32_e32 v35, vcc, 0, v13, vcc
	global_store_short v[34:35], v36, off offset:3072
	s_mov_b32 s17, 0x35be000
	v_rcp_f32_e32 v35, v32
	s_nop 0
	v_mul_f32_e32 v31, v31, v35
	v_mul_f32_e32 v31, v27, v31
	v_lshlrev_b32_e32 v27, 16, v58
	v_mul_f32_e32 v28, 0xbfb8aa3b, v27
	v_exp_f32_e32 v28, v28
	v_add_co_u32_e32 v34, vcc, s17, v12
	v_cvt_pk_bf16_f32 v31, v31, s0
	s_nop 0
	v_addc_co_u32_e32 v35, vcc, 0, v13, vcc
	v_add_f32_e32 v28, 1.0, v28
	global_store_short v[34:35], v31, off offset:1024
	s_mov_b32 s17, 0x35c1000
	v_rcp_f32_e32 v32, v28
	s_nop 0
	v_mul_f32_e32 v27, v27, v32
	v_mul_f32_e32 v27, v25, v27
	v_lshlrev_b32_e32 v25, 16, v59
	v_mul_f32_e32 v26, 0xbfb8aa3b, v25
	v_exp_f32_e32 v26, v26
	v_add_co_u32_e32 v34, vcc, s17, v12
	v_cvt_pk_bf16_f32 v27, v27, s0
	s_nop 0
	v_addc_co_u32_e32 v35, vcc, 0, v13, vcc
	v_add_f32_e32 v26, 1.0, v26
	global_store_short v[34:35], v27, off offset:3072
	s_mov_b32 s17, 0x35c5000
	v_rcp_f32_e32 v28, v26
	s_nop 0
	v_mul_f32_e32 v25, v25, v28
	v_mul_f32_e32 v25, v22, v25
	v_lshlrev_b32_e32 v22, 16, v60
	v_mul_f32_e32 v23, 0xbfb8aa3b, v22
	v_exp_f32_e32 v23, v23
	v_add_co_u32_e32 v26, vcc, s17, v12
	v_cvt_pk_bf16_f32 v25, v25, s0
	s_nop 0
	v_addc_co_u32_e32 v27, vcc, 0, v13, vcc
	v_add_f32_e32 v23, 1.0, v23
	global_store_short v[26:27], v25, off offset:1024
	s_mov_b32 s17, 0x35c8000
	v_rcp_f32_e32 v26, v23
	s_nop 0
	v_mul_f32_e32 v22, v22, v26
	v_mul_f32_e32 v22, v20, v22
	v_lshlrev_b32_e32 v20, 16, v61
	v_mul_f32_e32 v21, 0xbfb8aa3b, v20
	v_exp_f32_e32 v21, v21
	v_cvt_pk_bf16_f32 v25, v22, s0
	v_add_co_u32_e32 v22, vcc, s17, v12
	v_add_f32_e32 v21, 1.0, v21
	s_nop 0
	v_addc_co_u32_e32 v23, vcc, 0, v13, vcc
	global_store_short v[22:23], v25, off offset:3072
	s_mov_b32 s17, 0x35cc000
	v_rcp_f32_e32 v23, v21
	s_nop 0
	v_mul_f32_e32 v20, v20, v23
	v_mul_f32_e32 v20, v18, v20
	v_lshlrev_b32_e32 v18, 16, v33
	v_mul_f32_e32 v19, 0xbfb8aa3b, v18
	v_exp_f32_e32 v19, v19
	v_cvt_pk_bf16_f32 v22, v20, s0
	v_add_co_u32_e32 v20, vcc, s17, v12
	v_add_f32_e32 v19, 1.0, v19
	s_nop 0
	v_addc_co_u32_e32 v21, vcc, 0, v13, vcc
	global_store_short v[20:21], v22, off offset:1024
	s_mov_b32 s17, 0x35cf000
	v_rcp_f32_e32 v21, v19
	s_nop 0
	v_mul_f32_e32 v18, v18, v21
	v_mul_f32_e32 v18, v16, v18
	v_lshlrev_b32_e32 v16, 16, v29
	v_mul_f32_e32 v17, 0xbfb8aa3b, v16
	v_exp_f32_e32 v17, v17
	v_cvt_pk_bf16_f32 v20, v18, s0
	v_add_co_u32_e32 v18, vcc, s17, v12
	v_add_f32_e32 v17, 1.0, v17
	s_nop 0
	v_addc_co_u32_e32 v19, vcc, 0, v13, vcc
	global_store_short v[18:19], v20, off offset:3072
	s_mov_b32 s17, 0x35d3000
	v_rcp_f32_e32 v19, v17
	s_nop 0
	v_mul_f32_e32 v16, v16, v19
	v_mul_f32_e32 v16, v14, v16
	v_mul_f32_e32 v14, 0xbfb8aa3b, v11
	v_exp_f32_e32 v14, v14
	v_cvt_pk_bf16_f32 v18, v16, s0
	v_add_co_u32_e32 v16, vcc, s17, v12
	v_add_f32_e32 v14, 1.0, v14
	s_nop 0
	v_addc_co_u32_e32 v17, vcc, 0, v13, vcc
	v_div_scale_f32 v15, s[18:19], v14, v14, v11
	global_store_short v[16:17], v18, off offset:1024
	v_rcp_f32_e32 v16, v15
	s_mov_b32 s17, 0x35d6000
	v_fma_f32 v17, -v15, v16, 1.0
	v_fmac_f32_e32 v16, v17, v16
	v_div_scale_f32 v17, vcc, v11, v14, v11
	v_mul_f32_e32 v18, v17, v16
	v_fma_f32 v19, -v15, v18, v17
	v_fmac_f32_e32 v18, v19, v16
	v_fma_f32 v15, -v15, v18, v17
	v_div_fmas_f32 v15, v15, v16, v18
	v_div_fixup_f32 v11, v15, v14, v11
	v_mul_f32_e32 v11, v0, v11
	v_add_co_u32_e32 v14, vcc, s17, v12
	v_cvt_pk_bf16_f32 v11, v11, s0
	s_nop 0
	v_addc_co_u32_e32 v15, vcc, 0, v13, vcc
	global_store_short v[14:15], v11, off offset:3072
	v_mov_b32_e32 v11, v10
	v_fmac_f32_e32 v11, v0, v3
	s_waitcnt vmcnt(14)
	v_lshlrev_b32_e32 v0, 16, v24
	v_mul_f32_e32 v3, 0xbfb8aa3b, v0
	v_exp_f32_e32 v3, v3
	s_nop 0
	v_add_f32_e32 v3, 1.0, v3
	s_mov_b64 s[18:19], 0x38000
	v_lshl_add_u64 v[6:7], v[6:7], 0, s[18:19]
	v_rcp_f32_e32 v14, v3
	s_nop 0
	v_mul_f32_e32 v0, v0, v14
	v_mul_f32_e32 v0, v11, v0
	v_cvt_pk_bf16_f32 v0, v0, s0
	v_add_co_u32_e32 v12, vcc, 0x35da000, v12
	s_add_i32 s0, s0, 16
	s_nop 0
	v_addc_co_u32_e32 v13, vcc, 0, v13, vcc
	s_cmp_gt_u32 s0, 47
	global_store_short v[12:13], v0, off offset:1024
	s_cbranch_scc0 .LBB0_191
	v_cmp_ne_u64_e32 vcc, 0, v[4:5]
	s_and_saveexec_b64 s[18:19], vcc
	s_cbranch_execz .LBB0_194
	global_store_dword v[4:5], v11, off

.Lsg2_tail:
	s_waitcnt vmcnt(21)
	v_mfma_f32_16x16x32_bf16 v[6:9], v[20:23], v[24:27], v[6:9]
	v_mfma_f32_16x16x32_bf16 v[2:5], v[20:23], v[32:35], v[2:5]
	s_waitcnt vmcnt(18)
	v_mfma_f32_16x16x32_bf16 v[6:9], v[96:99], v[100:103], v[6:9]
	v_mfma_f32_16x16x32_bf16 v[2:5], v[96:99], v[104:107], v[2:5]
	s_waitcnt vmcnt(15)
	v_mfma_f32_16x16x32_bf16 v[6:9], v[108:111], v[112:115], v[6:9]
	v_mfma_f32_16x16x32_bf16 v[2:5], v[108:111], v[116:119], v[2:5]
	s_waitcnt vmcnt(12)
	v_mfma_f32_16x16x32_bf16 v[6:9], v[120:123], v[124:127], v[6:9]
	v_mfma_f32_16x16x32_bf16 v[2:5], v[120:123], v[128:131], v[2:5]
	s_waitcnt vmcnt(9)
	v_mfma_f32_16x16x32_bf16 v[6:9], v[132:135], v[136:139], v[6:9]
	v_mfma_f32_16x16x32_bf16 v[2:5], v[132:135], v[140:143], v[2:5]
	s_waitcnt vmcnt(6)
	v_mfma_f32_16x16x32_bf16 v[6:9], v[144:147], v[148:151], v[6:9]
	v_mfma_f32_16x16x32_bf16 v[2:5], v[144:147], v[152:155], v[2:5]
	s_waitcnt vmcnt(3)
	v_mfma_f32_16x16x32_bf16 v[6:9], v[156:159], v[160:163], v[6:9]
	v_mfma_f32_16x16x32_bf16 v[2:5], v[156:159], v[164:167], v[2:5]
	s_waitcnt vmcnt(0)
	v_mfma_f32_16x16x32_bf16 v[6:9], v[172:175], v[176:179], v[6:9]
	v_mfma_f32_16x16x32_bf16 v[2:5], v[172:175], v[180:183], v[2:5]
	s_add_i32 s0, s62, 0xfffffe7e
	s_lshl_b32 s17, s0, 4
	s_and_b32 s17, s17, 0x70
	v_lshrrev_b32_e32 v0, 2, v30
	v_and_or_b32 v0, v0, 12, s17
	v_or_b32_e32 v0, 0x4000, v0
	v_mul_u32_u24_e32 v0, 0x1c00, v0
	s_lshl_b32 s0, s0, 5
	v_lshlrev_b32_e32 v0, 1, v0
	s_and_b32 s0, s0, 0xffffff00
	v_lshl_add_u64 v[12:13], s[4:5], 0, v[0:1]
	v_ashrrev_i32_e32 v11, 31, v10
	v_lshl_add_u64 v[12:13], s[0:1], 1, v[12:13]
	v_lshl_add_u64 v[10:11], v[10:11], 1, v[12:13]
	v_lshlrev_b32_e32 v0, 1, v18
	v_lshl_add_u64 v[10:11], v[10:11], 0, v[0:1]
	global_load_ushort v0, v[10:11], off offset:1024
	s_waitcnt vmcnt(0)
	v_lshlrev_b32_e32 v0, 16, v0
	v_mul_f32_e32 v12, 0xbfb8aa3b, v0
	v_exp_f32_e32 v12, v12
	s_nop 0
	v_add_f32_e32 v12, 1.0, v12
	v_rcp_f32_e32 v14, v12
	s_nop 0
	v_mul_f32_e32 v0, v0, v14
	v_mul_f32_e32 v0, v6, v0
	v_cvt_pk_bf16_f32 v0, v0, s0
	global_store_short v[10:11], v0, off offset:2048
	global_load_ushort v0, v[10:11], off offset:1056
	s_waitcnt vmcnt(0)
	v_lshlrev_b32_e32 v0, 16, v0
	v_mul_f32_e32 v6, 0xbfb8aa3b, v0
	v_exp_f32_e32 v6, v6
	s_nop 0
	v_add_f32_e32 v6, 1.0, v6
	s_mov_b64 s[18:19], 0x3c00
	v_rcp_f32_e32 v13, v6
	s_nop 0
	v_mul_f32_e32 v0, v0, v13
	v_mul_f32_e32 v0, v2, v0
	v_cvt_pk_bf16_f32 v0, v0, s0
	s_movk_i32 s0, 0x3000
	v_add_co_u32_e32 v14, vcc, s0, v10
	global_store_short v[10:11], v0, off offset:2080
	s_nop 0
	v_addc_co_u32_e32 v15, vcc, 0, v11, vcc
	global_load_ushort v0, v[14:15], off offset:3072
	v_lshl_add_u64 v[12:13], v[10:11], 0, s[18:19]
	s_waitcnt vmcnt(0)
	v_lshlrev_b32_e32 v0, 16, v0
	v_mul_f32_e32 v2, 0xbfb8aa3b, v0
	v_exp_f32_e32 v2, v2
	s_nop 0
	v_add_f32_e32 v2, 1.0, v2
	v_rcp_f32_e32 v14, v2
	s_nop 0
	v_mul_f32_e32 v0, v0, v14
	v_mul_f32_e32 v0, v7, v0
	v_cvt_pk_bf16_f32 v0, v0, s0
	global_store_short v[12:13], v0, off offset:1024
	global_load_ushort v0, v[12:13], off offset:32
	s_waitcnt vmcnt(0)
	v_lshlrev_b32_e32 v0, 16, v0
	v_mul_f32_e32 v2, 0xbfb8aa3b, v0
	v_exp_f32_e32 v2, v2
	s_nop 0
	v_add_f32_e32 v2, 1.0, v2
	s_mov_b64 s[18:19], 0x7400
	v_rcp_f32_e32 v7, v2
	s_nop 0
	v_mul_f32_e32 v0, v0, v7
	v_mul_f32_e32 v0, v3, v0
	v_cvt_pk_bf16_f32 v0, v0, s0
	s_movk_i32 s0, 0x7000
	v_add_co_u32_e32 v6, vcc, s0, v10
	global_store_short v[12:13], v0, off offset:1056
	s_nop 0
	v_addc_co_u32_e32 v7, vcc, 0, v11, vcc
	global_load_ushort v0, v[6:7], off offset:1024
	v_lshl_add_u64 v[2:3], v[10:11], 0, s[18:19]
	s_waitcnt vmcnt(0)
	v_lshlrev_b32_e32 v0, 16, v0
	v_mul_f32_e32 v6, 0xbfb8aa3b, v0
	v_exp_f32_e32 v6, v6
	s_nop 0
	v_add_f32_e32 v6, 1.0, v6
	v_rcp_f32_e32 v12, v6
	s_nop 0
	v_mul_f32_e32 v0, v0, v12
	v_mul_f32_e32 v0, v8, v0
	v_cvt_pk_bf16_f32 v0, v0, s0
	global_store_short v[2:3], v0, off offset:1024
	global_load_ushort v0, v[2:3], off offset:32
	s_waitcnt vmcnt(0)
	v_lshlrev_b32_e32 v0, 16, v0
	v_mul_f32_e32 v6, 0xbfb8aa3b, v0
	v_exp_f32_e32 v6, v6
	s_nop 0
	v_add_f32_e32 v6, 1.0, v6
	s_mov_b64 s[18:19], 0xac00
	v_rcp_f32_e32 v8, v6
	s_nop 0
	v_mul_f32_e32 v0, v0, v8
	v_mul_f32_e32 v0, v4, v0
	v_cvt_pk_bf16_f32 v0, v0, s0
	s_mov_b32 s0, 0xa000
	v_add_co_u32_e32 v6, vcc, s0, v10
	global_store_short v[2:3], v0, off offset:1056
	s_nop 0
	v_addc_co_u32_e32 v7, vcc, 0, v11, vcc
	global_load_ushort v0, v[6:7], off offset:3072
	v_lshl_add_u64 v[2:3], v[10:11], 0, s[18:19]
	s_waitcnt vmcnt(0)
	v_lshlrev_b32_e32 v0, 16, v0
	v_mul_f32_e32 v4, 0xbfb8aa3b, v0
	v_exp_f32_e32 v4, v4
	s_nop 0
	v_add_f32_e32 v4, 1.0, v4
	v_rcp_f32_e32 v7, v4
	s_nop 0
	v_mul_f32_e32 v0, v0, v7
	v_mul_f32_e32 v0, v9, v0
	v_cvt_pk_bf16_f32 v0, v0, s0
	global_store_short v[2:3], v0, off offset:1024
	global_load_ushort v0, v[2:3], off offset:32
	s_waitcnt vmcnt(0)
	v_lshlrev_b32_e32 v0, 16, v0
	v_mul_f32_e32 v4, 0xbfb8aa3b, v0
	v_exp_f32_e32 v4, v4
	s_nop 0
	v_add_f32_e32 v4, 1.0, v4
	v_rcp_f32_e32 v7, v4
	s_nop 0
	v_mul_f32_e32 v0, v0, v7
	v_mul_f32_e32 v0, v5, v0
	v_cvt_pk_bf16_f32 v0, v0, s0
	global_store_short v[2:3], v0, off offset:1056

.LBB0_374:
	s_or_b64 exec, exec, s[26:27]
	s_waitcnt vmcnt(1) lgkmcnt(0)
	v_add_f32_e32 v76, v8, v76
	v_mul_f32_e32 v76, 0xbfb8aa3b, v76
	v_exp_f32_e32 v76, v76
	v_add_f32_e32 v77, v9, v77
	v_mul_f32_e32 v77, 0xbfb8aa3b, v77
	v_exp_f32_e32 v77, v77
	v_add_f32_e32 v76, 1.0, v76
	v_add_f32_e32 v77, 1.0, v77
	v_rcp_f32_e32 v76, v76
	s_nop 0
	v_div_scale_f32 v100, s[4:5], v77, v77, 1.0
	v_rcp_f32_e32 v101, v100
	v_add_f32_e32 v75, v7, v75
	v_mul_f32_e32 v75, 0xbfb8aa3b, v75
	v_mul_f32_e32 v76, v76, v97
	v_fma_f32 v97, -v100, v101, 1.0
	v_exp_f32_e32 v75, v75
	s_waitcnt vmcnt(0)
	v_lshlrev_b32_e32 v105, 16, v83
	v_fmac_f32_e32 v101, v97, v101
	v_div_scale_f32 v97, vcc, 1.0, v77, 1.0
	v_mul_f32_e32 v76, v76, v105
	v_mul_f32_e32 v105, v97, v101
	v_fma_f32 v106, -v100, v105, v97
	v_fmac_f32_e32 v105, v106, v101
	v_add_f32_e32 v75, 1.0, v75
	v_fma_f32 v97, -v100, v105, v97
	v_div_scale_f32 v100, s[4:5], v75, v75, 1.0
	v_div_fmas_f32 v97, v97, v101, v105
	v_rcp_f32_e32 v101, v100
	v_div_fixup_f32 v77, v97, v77, 1.0
	v_mul_f32_e32 v97, 0x3fb8aa3b, v99
	v_exp_f32_e32 v109, v97
	v_fma_f32 v97, -v100, v101, 1.0
	v_fmac_f32_e32 v101, v97, v101
	v_div_scale_f32 v97, vcc, 1.0, v75, 1.0
	v_add_f32_e32 v74, v6, v74
	v_mul_f32_e32 v99, v97, v101
	v_mul_f32_e32 v74, 0xbfb8aa3b, v74
	v_fma_f32 v105, -v100, v99, v97
	v_exp_f32_e32 v74, v74
	v_fmac_f32_e32 v99, v105, v101
	v_fma_f32 v97, -v100, v99, v97
	v_div_fmas_f32 v97, v97, v101, v99
	v_div_fixup_f32 v75, v97, v75, 1.0
	v_add_f32_e32 v74, 1.0, v74
	v_and_b32_e32 v97, 0xffff0000, v82
	v_mul_f32_e32 v75, v75, v96
	v_div_scale_f32 v96, s[4:5], v74, v74, 1.0
	v_mul_f32_e32 v75, v75, v97
	v_rcp_f32_e32 v97, v96
	v_mul_f32_e32 v80, 0x3fb8aa3b, v80
	v_exp_f32_e32 v108, v80
	v_lshlrev_b32_e32 v80, 16, v82
	v_fma_f32 v82, -v96, v97, 1.0
	v_fmac_f32_e32 v97, v82, v97
	v_div_scale_f32 v82, vcc, 1.0, v74, 1.0
	v_mul_f32_e32 v99, v82, v97
	v_fma_f32 v100, -v96, v99, v82
	v_fmac_f32_e32 v99, v100, v97
	v_fma_f32 v82, -v96, v99, v82
	v_mul_f32_e32 v79, 0x3fb8aa3b, v79
	v_mul_f32_e32 v78, 0x3fb8aa3b, v78
	v_div_fmas_f32 v82, v82, v97, v99
	v_exp_f32_e32 v107, v79
	v_exp_f32_e32 v106, v78
	v_div_fixup_f32 v74, v82, v74, 1.0
	v_and_b32_e32 v79, 0xffff0000, v83
	v_mul_f32_e32 v77, v77, v81
	v_mul_f32_e32 v74, v74, v95
	v_mul_f32_e32 v77, v77, v79
	v_lshlrev_b64 v[78:79], 2, v[84:85]
	v_mul_f32_e32 v74, v74, v80
	v_lshl_add_u64 v[80:81], v[142:143], 0, v[78:79]
	v_lshl_add_u64 v[78:79], v[144:145], 0, v[78:79]
	global_store_dwordx4 v[80:81], v[106:109], off
	global_store_dwordx4 v[78:79], v[74:77], off

.LBB0_376:
	v_add_u32_e32 v95, s49, v139
	v_ashrrev_i32_e32 v74, 5, v95
	v_add_u32_e32 v84, s48, v74
	s_movk_i32 s4, 0x4080
	v_cmp_gt_i32_e32 vcc, s4, v84
	s_and_saveexec_b64 s[10:11], vcc
	s_cbranch_execz .LBB0_402
	v_ashrrev_i32_e32 v85, 31, v84
	v_lshlrev_b64 v[76:77], 10, v[84:85]
	v_lshl_add_u64 v[76:77], v[140:141], 0, v[76:77]
	global_load_dwordx2 v[82:83], v[76:77], off
	v_mad_u64_u32 v[74:75], s[4:5], v74, s33, v[138:139]
	ds_read_b128 v[78:81], v74
	ds_read_b128 v[74:77], v74 offset:512
	s_movk_i32 s4, 0x3fff
	v_cmp_lt_i32_e32 vcc, s4, v84
	v_and_b32_e32 v96, 0xfff, v84
	s_waitcnt vmcnt(2) lgkmcnt(1)
	v_add_f32_e32 v78, v2, v78
	v_mul_f32_e32 v78, 0xbfb8aa3b, v78
	v_exp_f32_e32 v78, v78
	s_nop 0
	v_add_f32_e32 v78, 1.0, v78
	v_cmp_ne_u32_e64 s[4:5], 0, v96
	s_or_b64 s[24:25], vcc, s[4:5]
	v_mov_b32_e32 v96, 1.0
	v_rcp_f32_e32 v78, v78
	s_nop 0
	v_mul_f32_e32 v78, 0xc1000000, v78
	v_mul_f32_e32 v78, v146, v78
	s_and_saveexec_b64 s[26:27], s[24:25]
	s_cbranch_execz .LBB0_383
	v_add_f32_e32 v97, v78, v78
	s_mov_b32 s4, 0xbdcccccd
	v_cmp_nlt_f32_e32 vcc, s4, v97
	s_and_saveexec_b64 s[4:5], vcc
	s_xor_b64 s[4:5], exec, s[4:5]
	v_mul_f32_e32 v96, 0x3fb8aa3b, v97
	v_exp_f32_e32 v96, v96
	s_nop 0
	v_sub_f32_e32 v96, 1.0, v96
	s_andn2_saveexec_b64 s[4:5], s[4:5]
	v_fmamk_f32 v96, v97, 0x3d2aaaab, v171
	v_fma_f32 v96, v97, v96, 0.5
	v_fma_f32 v96, v97, v96, 1.0
	v_mul_f32_e64 v96, v97, -v96
	s_or_b64 exec, exec, s[4:5]
	s_mov_b32 s4, 0xf800000
	v_mul_f32_e32 v97, 0x4f800000, v96
	v_cmp_gt_f32_e32 vcc, s4, v96
	s_nop 1
	v_cndmask_b32_e32 v96, v96, v97, vcc
	v_sqrt_f32_e32 v97, v96
	s_nop 0
	v_add_u32_e32 v99, -1, v97
	v_fma_f32 v101, -v99, v97, v96
	v_add_u32_e32 v100, 1, v97
	v_cmp_ge_f32_e64 s[4:5], 0, v101
	s_nop 1
	v_cndmask_b32_e64 v99, v97, v99, s[4:5]
	v_fma_f32 v97, -v100, v97, v96
	v_cmp_lt_f32_e64 s[4:5], 0, v97
	s_nop 1
	v_cndmask_b32_e64 v97, v99, v100, s[4:5]
	v_mul_f32_e32 v99, 0x37800000, v97
	v_cndmask_b32_e32 v97, v97, v99, vcc
	v_cmp_class_f32_e32 vcc, v96, v200
	s_nop 1
	v_cndmask_b32_e32 v96, v97, v96, vcc
.LBB0_383:
	s_or_b64 exec, exec, s[26:27]
	v_add_f32_e32 v79, v3, v79
	v_mul_f32_e32 v79, 0xbfb8aa3b, v79
	v_exp_f32_e32 v79, v79
	v_lshlrev_b64 v[84:85], 9, v[84:85]
	v_mov_b32_e32 v97, 1.0
	v_add_f32_e32 v79, 1.0, v79
	v_rcp_f32_e32 v79, v79
	s_nop 0
	v_mul_f32_e32 v79, 0xc1000000, v79
	v_mul_f32_e32 v79, v147, v79
	s_and_saveexec_b64 s[26:27], s[24:25]
	s_cbranch_execz .LBB0_389
	v_add_f32_e32 v99, v79, v79
	s_mov_b32 s4, 0xbdcccccd
	v_cmp_nlt_f32_e32 vcc, s4, v99
	s_and_saveexec_b64 s[4:5], vcc
	s_xor_b64 s[4:5], exec, s[4:5]
	v_mul_f32_e32 v97, 0x3fb8aa3b, v99
	v_exp_f32_e32 v97, v97
	s_nop 0
	v_sub_f32_e32 v97, 1.0, v97
	s_andn2_saveexec_b64 s[4:5], s[4:5]
	v_fmamk_f32 v97, v99, 0x3d2aaaab, v171
	v_fma_f32 v97, v99, v97, 0.5
	v_fma_f32 v97, v99, v97, 1.0
	v_mul_f32_e64 v97, v99, -v97
	s_or_b64 exec, exec, s[4:5]
	s_mov_b32 s4, 0xf800000
	v_mul_f32_e32 v99, 0x4f800000, v97
	v_cmp_gt_f32_e32 vcc, s4, v97
	s_nop 1
	v_cndmask_b32_e32 v97, v97, v99, vcc
	v_sqrt_f32_e32 v99, v97
	s_nop 0
	v_add_u32_e32 v100, -1, v99
	v_fma_f32 v105, -v100, v99, v97
	v_add_u32_e32 v101, 1, v99
	v_cmp_ge_f32_e64 s[4:5], 0, v105
	s_nop 1
	v_cndmask_b32_e64 v100, v99, v100, s[4:5]
	v_fma_f32 v99, -v101, v99, v97
	v_cmp_lt_f32_e64 s[4:5], 0, v99
	s_nop 1
	v_cndmask_b32_e64 v99, v100, v101, s[4:5]
	v_mul_f32_e32 v100, 0x37800000, v99
	v_cndmask_b32_e32 v99, v99, v100, vcc
	v_cmp_class_f32_e32 vcc, v97, v200
	s_nop 1
	v_cndmask_b32_e32 v97, v99, v97, vcc
.LBB0_389:
	s_or_b64 exec, exec, s[26:27]
	v_add_f32_e32 v80, v4, v80
	v_mul_f32_e32 v80, 0xbfb8aa3b, v80
	v_exp_f32_e32 v80, v80
	v_mov_b32_e32 v99, 1.0
	v_add_f32_e32 v80, 1.0, v80
	v_rcp_f32_e32 v80, v80
	s_nop 0
	v_mul_f32_e32 v80, 0xc1000000, v80
	v_mul_f32_e32 v80, v148, v80
	s_and_saveexec_b64 s[26:27], s[24:25]
	s_cbranch_execz .LBB0_395
	v_add_f32_e32 v100, v80, v80
	s_mov_b32 s4, 0xbdcccccd
	v_cmp_nlt_f32_e32 vcc, s4, v100
	s_and_saveexec_b64 s[4:5], vcc
	s_xor_b64 s[4:5], exec, s[4:5]
	v_mul_f32_e32 v99, 0x3fb8aa3b, v100
	v_exp_f32_e32 v99, v99
	s_nop 0
	v_sub_f32_e32 v99, 1.0, v99
	s_andn2_saveexec_b64 s[4:5], s[4:5]
	v_fmamk_f32 v99, v100, 0x3d2aaaab, v171
	v_fma_f32 v99, v100, v99, 0.5
	v_fma_f32 v99, v100, v99, 1.0
	v_mul_f32_e64 v99, v100, -v99
	s_or_b64 exec, exec, s[4:5]
	s_mov_b32 s4, 0xf800000
	v_mul_f32_e32 v100, 0x4f800000, v99
	v_cmp_gt_f32_e32 vcc, s4, v99
	s_nop 1
	v_cndmask_b32_e32 v99, v99, v100, vcc
	v_sqrt_f32_e32 v100, v99
	s_nop 0
	v_add_u32_e32 v101, -1, v100
	v_fma_f32 v106, -v101, v100, v99
	v_add_u32_e32 v105, 1, v100
	v_cmp_ge_f32_e64 s[4:5], 0, v106
	s_nop 1
	v_cndmask_b32_e64 v101, v100, v101, s[4:5]
	v_fma_f32 v100, -v105, v100, v99
	v_cmp_lt_f32_e64 s[4:5], 0, v100
	s_nop 1
	v_cndmask_b32_e64 v100, v101, v105, s[4:5]
	v_mul_f32_e32 v101, 0x37800000, v100
	v_cndmask_b32_e32 v100, v100, v101, vcc
	v_cmp_class_f32_e32 vcc, v99, v200
	s_nop 1
	v_cndmask_b32_e32 v99, v100, v99, vcc
.LBB0_395:
	s_or_b64 exec, exec, s[26:27]
	v_add_f32_e32 v81, v5, v81
	v_mul_f32_e32 v81, 0xbfb8aa3b, v81
	v_exp_f32_e32 v81, v81
	s_nop 0
	v_add_f32_e32 v100, 1.0, v81
	v_mov_b32_e32 v81, 1.0
	v_rcp_f32_e32 v100, v100
	s_nop 0
	v_mul_f32_e32 v100, 0xc1000000, v100
	v_mul_f32_e32 v100, v149, v100
	s_and_saveexec_b64 s[26:27], s[24:25]
	s_cbranch_execz .LBB0_401
	v_add_f32_e32 v101, v100, v100
	s_mov_b32 s4, 0xbdcccccd
	v_cmp_nlt_f32_e32 vcc, s4, v101
	s_and_saveexec_b64 s[4:5], vcc
	s_xor_b64 s[4:5], exec, s[4:5]
	v_mul_f32_e32 v81, 0x3fb8aa3b, v101
	v_exp_f32_e32 v81, v81
	s_nop 0
	v_sub_f32_e32 v81, 1.0, v81
	s_andn2_saveexec_b64 s[4:5], s[4:5]
	v_fmamk_f32 v81, v101, 0x3d2aaaab, v171
	v_fma_f32 v81, v101, v81, 0.5
	v_fma_f32 v81, v101, v81, 1.0
	v_mul_f32_e64 v81, v101, -v81
	s_or_b64 exec, exec, s[4:5]
	s_mov_b32 s4, 0xf800000
	v_mul_f32_e32 v101, 0x4f800000, v81
	v_cmp_gt_f32_e32 vcc, s4, v81
	s_nop 1
	v_cndmask_b32_e32 v81, v81, v101, vcc
	v_sqrt_f32_e32 v101, v81
	s_nop 0
	v_add_u32_e32 v105, -1, v101
	v_fma_f32 v107, -v105, v101, v81
	v_add_u32_e32 v106, 1, v101
	v_cmp_ge_f32_e64 s[4:5], 0, v107
	s_nop 1
	v_cndmask_b32_e64 v105, v101, v105, s[4:5]
	v_fma_f32 v101, -v106, v101, v81
	v_cmp_lt_f32_e64 s[4:5], 0, v101
	s_nop 1
	v_cndmask_b32_e64 v101, v105, v106, s[4:5]
	v_mul_f32_e32 v105, 0x37800000, v101
	v_cndmask_b32_e32 v101, v101, v105, vcc
	v_cmp_class_f32_e32 vcc, v81, v200
	s_nop 1
	v_cndmask_b32_e32 v81, v101, v81, vcc
.LBB0_401:
	s_or_b64 exec, exec, s[26:27]
	s_waitcnt vmcnt(1) lgkmcnt(0)
	v_add_f32_e32 v76, v8, v76
	v_mul_f32_e32 v76, 0xbfb8aa3b, v76
	v_exp_f32_e32 v76, v76
	v_add_f32_e32 v77, v9, v77
	v_mul_f32_e32 v77, 0xbfb8aa3b, v77
	v_exp_f32_e32 v77, v77
	v_add_f32_e32 v76, 1.0, v76
	v_add_f32_e32 v77, 1.0, v77
	v_rcp_f32_e32 v76, v76
	s_nop 0
	v_div_scale_f32 v101, s[4:5], v77, v77, 1.0
	v_rcp_f32_e32 v105, v101
	v_add_f32_e32 v75, v7, v75
	v_mul_f32_e32 v75, 0xbfb8aa3b, v75
	v_mul_f32_e32 v76, v76, v99
	v_fma_f32 v99, -v101, v105, 1.0
	v_exp_f32_e32 v75, v75
	s_waitcnt vmcnt(0)
	v_lshlrev_b32_e32 v106, 16, v83
	v_fmac_f32_e32 v105, v99, v105
	v_div_scale_f32 v99, vcc, 1.0, v77, 1.0
	v_mul_f32_e32 v76, v76, v106
	v_mul_f32_e32 v106, v99, v105
	v_fma_f32 v107, -v101, v106, v99
	v_fmac_f32_e32 v106, v107, v105
	v_add_f32_e32 v75, 1.0, v75
	v_fma_f32 v99, -v101, v106, v99
	v_div_scale_f32 v101, s[4:5], v75, v75, 1.0
	v_div_fmas_f32 v99, v99, v105, v106
	v_rcp_f32_e32 v105, v101
	v_div_fixup_f32 v77, v99, v77, 1.0
	v_mul_f32_e32 v99, 0x3fb8aa3b, v100
	v_exp_f32_e32 v109, v99
	v_fma_f32 v99, -v101, v105, 1.0
	v_fmac_f32_e32 v105, v99, v105
	v_div_scale_f32 v99, vcc, 1.0, v75, 1.0
	v_add_f32_e32 v74, v6, v74
	v_mul_f32_e32 v100, v99, v105
	v_mul_f32_e32 v74, 0xbfb8aa3b, v74
	v_fma_f32 v106, -v101, v100, v99
	v_exp_f32_e32 v74, v74
	v_fmac_f32_e32 v100, v106, v105
	v_fma_f32 v99, -v101, v100, v99
	v_div_fmas_f32 v99, v99, v105, v100
	v_div_fixup_f32 v75, v99, v75, 1.0
	v_add_f32_e32 v74, 1.0, v74
	v_and_b32_e32 v99, 0xffff0000, v82
	v_mul_f32_e32 v75, v75, v97
	v_div_scale_f32 v97, s[4:5], v74, v74, 1.0
	v_mul_f32_e32 v75, v75, v99
	v_rcp_f32_e32 v99, v97
	v_mul_f32_e32 v80, 0x3fb8aa3b, v80
	v_exp_f32_e32 v108, v80
	v_lshlrev_b32_e32 v80, 16, v82
	v_fma_f32 v82, -v97, v99, 1.0
	v_fmac_f32_e32 v99, v82, v99
	v_div_scale_f32 v82, vcc, 1.0, v74, 1.0
	v_mul_f32_e32 v100, v82, v99
	v_fma_f32 v101, -v97, v100, v82
	v_fmac_f32_e32 v100, v101, v99
	v_fma_f32 v82, -v97, v100, v82
	v_mul_f32_e32 v79, 0x3fb8aa3b, v79
	v_mul_f32_e32 v78, 0x3fb8aa3b, v78
	v_div_fmas_f32 v82, v82, v99, v100
	v_exp_f32_e32 v107, v79
	v_exp_f32_e32 v106, v78
	v_div_fixup_f32 v74, v82, v74, 1.0
	v_and_b32_e32 v79, 0xffff0000, v83
	v_mul_f32_e32 v77, v77, v81
	v_mul_f32_e32 v74, v74, v96
	v_mul_f32_e32 v77, v77, v79
	v_lshlrev_b64 v[78:79], 2, v[84:85]
	v_mul_f32_e32 v74, v74, v80
	v_lshl_add_u64 v[80:81], v[142:143], 0, v[78:79]
	v_lshl_add_u64 v[78:79], v[144:145], 0, v[78:79]
	global_store_dwordx4 v[80:81], v[106:109], off
	global_store_dwordx4 v[78:79], v[74:77], off
.LBB0_402:
	s_or_b64 exec, exec, s[10:11]
	s_nop 0
	v_add_u32_e32 v74, 0x200, v95
	v_ashrrev_i32_e32 v74, 5, v74
	v_add_u32_e32 v84, s48, v74
	s_movk_i32 s4, 0x4080
	v_cmp_gt_i32_e32 vcc, s4, v84
	s_and_saveexec_b64 s[10:11], vcc
	s_cbranch_execz .LBB0_375
	v_ashrrev_i32_e32 v85, 31, v84
	v_lshlrev_b64 v[76:77], 10, v[84:85]
	v_lshl_add_u64 v[76:77], v[140:141], 0, v[76:77]
	global_load_dwordx2 v[82:83], v[76:77], off
	v_mad_u64_u32 v[74:75], s[4:5], v74, s33, v[138:139]
	ds_read_b128 v[78:81], v74
	ds_read_b128 v[74:77], v74 offset:512
	s_movk_i32 s4, 0x3fff
	v_cmp_lt_i32_e32 vcc, s4, v84
	v_and_b32_e32 v95, 0xfff, v84
	s_waitcnt vmcnt(2) lgkmcnt(1)
	v_add_f32_e32 v78, v2, v78
	v_mul_f32_e32 v78, 0xbfb8aa3b, v78
	v_exp_f32_e32 v78, v78
	s_nop 0
	v_add_f32_e32 v78, 1.0, v78
	v_cmp_ne_u32_e64 s[4:5], 0, v95
	s_or_b64 s[24:25], vcc, s[4:5]
	v_mov_b32_e32 v95, 1.0
	v_rcp_f32_e32 v78, v78
	s_nop 0
	v_mul_f32_e32 v78, 0xc1000000, v78
	v_mul_f32_e32 v78, v146, v78
	s_and_saveexec_b64 s[26:27], s[24:25]
	s_cbranch_execz .LBB0_409
	v_add_f32_e32 v96, v78, v78
	s_mov_b32 s4, 0xbdcccccd
	v_cmp_nlt_f32_e32 vcc, s4, v96
	s_and_saveexec_b64 s[4:5], vcc
	s_xor_b64 s[4:5], exec, s[4:5]
	v_mul_f32_e32 v95, 0x3fb8aa3b, v96
	v_exp_f32_e32 v95, v95
	s_nop 0
	v_sub_f32_e32 v95, 1.0, v95
	s_andn2_saveexec_b64 s[4:5], s[4:5]
	v_fmamk_f32 v95, v96, 0x3d2aaaab, v171
	v_fma_f32 v95, v96, v95, 0.5
	v_fma_f32 v95, v96, v95, 1.0
	v_mul_f32_e64 v95, v96, -v95
	s_or_b64 exec, exec, s[4:5]
	s_mov_b32 s4, 0xf800000
	v_mul_f32_e32 v96, 0x4f800000, v95
	v_cmp_gt_f32_e32 vcc, s4, v95
	s_nop 1
	v_cndmask_b32_e32 v95, v95, v96, vcc
	v_sqrt_f32_e32 v96, v95
	s_nop 0
	v_add_u32_e32 v97, -1, v96
	v_fma_f32 v100, -v97, v96, v95
	v_add_u32_e32 v99, 1, v96
	v_cmp_ge_f32_e64 s[4:5], 0, v100
	s_nop 1
	v_cndmask_b32_e64 v97, v96, v97, s[4:5]
	v_fma_f32 v96, -v99, v96, v95
	v_cmp_lt_f32_e64 s[4:5], 0, v96
	s_nop 1
	v_cndmask_b32_e64 v96, v97, v99, s[4:5]
	v_mul_f32_e32 v97, 0x37800000, v96
	v_cndmask_b32_e32 v96, v96, v97, vcc
	v_cmp_class_f32_e32 vcc, v95, v200
	s_nop 1
	v_cndmask_b32_e32 v95, v96, v95, vcc
.LBB0_409:
	s_or_b64 exec, exec, s[26:27]
	v_add_f32_e32 v79, v3, v79
	v_mul_f32_e32 v79, 0xbfb8aa3b, v79
	v_exp_f32_e32 v79, v79
	v_lshlrev_b64 v[84:85], 9, v[84:85]
	v_mov_b32_e32 v96, 1.0
	v_add_f32_e32 v79, 1.0, v79
	v_rcp_f32_e32 v79, v79
	s_nop 0
	v_mul_f32_e32 v79, 0xc1000000, v79
	v_mul_f32_e32 v79, v147, v79
	s_and_saveexec_b64 s[26:27], s[24:25]
	s_cbranch_execz .LBB0_415
	v_add_f32_e32 v97, v79, v79
	s_mov_b32 s4, 0xbdcccccd
	v_cmp_nlt_f32_e32 vcc, s4, v97
	s_and_saveexec_b64 s[4:5], vcc
	s_xor_b64 s[4:5], exec, s[4:5]
	v_mul_f32_e32 v96, 0x3fb8aa3b, v97
	v_exp_f32_e32 v96, v96
	s_nop 0
	v_sub_f32_e32 v96, 1.0, v96
	s_andn2_saveexec_b64 s[4:5], s[4:5]
	v_fmamk_f32 v96, v97, 0x3d2aaaab, v171
	v_fma_f32 v96, v97, v96, 0.5
	v_fma_f32 v96, v97, v96, 1.0
	v_mul_f32_e64 v96, v97, -v96
	s_or_b64 exec, exec, s[4:5]
	s_mov_b32 s4, 0xf800000
	v_mul_f32_e32 v97, 0x4f800000, v96
	v_cmp_gt_f32_e32 vcc, s4, v96
	s_nop 1
	v_cndmask_b32_e32 v96, v96, v97, vcc
	v_sqrt_f32_e32 v97, v96
	s_nop 0
	v_add_u32_e32 v99, -1, v97
	v_fma_f32 v101, -v99, v97, v96
	v_add_u32_e32 v100, 1, v97
	v_cmp_ge_f32_e64 s[4:5], 0, v101
	s_nop 1
	v_cndmask_b32_e64 v99, v97, v99, s[4:5]
	v_fma_f32 v97, -v100, v97, v96
	v_cmp_lt_f32_e64 s[4:5], 0, v97
	s_nop 1
	v_cndmask_b32_e64 v97, v99, v100, s[4:5]
	v_mul_f32_e32 v99, 0x37800000, v97
	v_cndmask_b32_e32 v97, v97, v99, vcc
	v_cmp_class_f32_e32 vcc, v96, v200
	s_nop 1
	v_cndmask_b32_e32 v96, v97, v96, vcc
.LBB0_415:
	s_or_b64 exec, exec, s[26:27]
	v_add_f32_e32 v80, v4, v80
	v_mul_f32_e32 v80, 0xbfb8aa3b, v80
	v_exp_f32_e32 v80, v80
	v_mov_b32_e32 v97, 1.0
	v_add_f32_e32 v80, 1.0, v80
	v_rcp_f32_e32 v80, v80
	s_nop 0
	v_mul_f32_e32 v80, 0xc1000000, v80
	v_mul_f32_e32 v80, v148, v80
	s_and_saveexec_b64 s[26:27], s[24:25]
	s_cbranch_execz .LBB0_421
	v_add_f32_e32 v99, v80, v80
	s_mov_b32 s4, 0xbdcccccd
	v_cmp_nlt_f32_e32 vcc, s4, v99
	s_and_saveexec_b64 s[4:5], vcc
	s_xor_b64 s[4:5], exec, s[4:5]
	v_mul_f32_e32 v97, 0x3fb8aa3b, v99
	v_exp_f32_e32 v97, v97
	s_nop 0
	v_sub_f32_e32 v97, 1.0, v97
	s_andn2_saveexec_b64 s[4:5], s[4:5]
	v_fmamk_f32 v97, v99, 0x3d2aaaab, v171
	v_fma_f32 v97, v99, v97, 0.5
	v_fma_f32 v97, v99, v97, 1.0
	v_mul_f32_e64 v97, v99, -v97
	s_or_b64 exec, exec, s[4:5]
	s_mov_b32 s4, 0xf800000
	v_mul_f32_e32 v99, 0x4f800000, v97
	v_cmp_gt_f32_e32 vcc, s4, v97
	s_nop 1
	v_cndmask_b32_e32 v97, v97, v99, vcc
	v_sqrt_f32_e32 v99, v97
	s_nop 0
	v_add_u32_e32 v100, -1, v99
	v_fma_f32 v105, -v100, v99, v97
	v_add_u32_e32 v101, 1, v99
	v_cmp_ge_f32_e64 s[4:5], 0, v105
	s_nop 1
	v_cndmask_b32_e64 v100, v99, v100, s[4:5]
	v_fma_f32 v99, -v101, v99, v97
	v_cmp_lt_f32_e64 s[4:5], 0, v99
	s_nop 1
	v_cndmask_b32_e64 v99, v100, v101, s[4:5]
	v_mul_f32_e32 v100, 0x37800000, v99
	v_cndmask_b32_e32 v99, v99, v100, vcc
	v_cmp_class_f32_e32 vcc, v97, v200
	s_nop 1
	v_cndmask_b32_e32 v97, v99, v97, vcc
.LBB0_421:
	s_or_b64 exec, exec, s[26:27]
	v_add_f32_e32 v81, v5, v81
	v_mul_f32_e32 v81, 0xbfb8aa3b, v81
	v_exp_f32_e32 v81, v81
	s_nop 0
	v_add_f32_e32 v99, 1.0, v81
	v_mov_b32_e32 v81, 1.0
	v_rcp_f32_e32 v99, v99
	s_nop 0
	v_mul_f32_e32 v99, 0xc1000000, v99
	v_mul_f32_e32 v99, v149, v99
	s_and_saveexec_b64 s[26:27], s[24:25]
	s_cbranch_execz .LBB0_374
	v_add_f32_e32 v100, v99, v99
	s_mov_b32 s4, 0xbdcccccd
	v_cmp_nlt_f32_e32 vcc, s4, v100
	s_and_saveexec_b64 s[4:5], vcc
	s_xor_b64 s[4:5], exec, s[4:5]
	v_mul_f32_e32 v81, 0x3fb8aa3b, v100
	v_exp_f32_e32 v81, v81
	s_nop 0
	v_sub_f32_e32 v81, 1.0, v81
	s_andn2_saveexec_b64 s[4:5], s[4:5]
	s_cbranch_execz .LBB0_373
	v_fmamk_f32 v81, v100, 0x3d2aaaab, v171
	v_fma_f32 v81, v100, v81, 0.5
	v_fma_f32 v81, v100, v81, 1.0
	v_mul_f32_e64 v81, v100, -v81
	s_branch .LBB0_373

.LBB0_428:
	s_or_b64 exec, exec, s[26:27]
	s_waitcnt vmcnt(1) lgkmcnt(0)
	v_add_f32_e32 v12, v8, v12
	v_mul_f32_e32 v12, 0xbfb8aa3b, v12
	v_exp_f32_e32 v12, v12
	v_add_f32_e32 v13, v9, v13
	v_mul_f32_e32 v13, 0xbfb8aa3b, v13
	v_exp_f32_e32 v13, v13
	v_add_f32_e32 v12, 1.0, v12
	v_add_f32_e32 v13, 1.0, v13
	v_rcp_f32_e32 v12, v12
	s_nop 0
	v_div_scale_f32 v25, s[4:5], v13, v13, 1.0
	v_rcp_f32_e32 v26, v25
	v_add_f32_e32 v11, v7, v11
	v_mul_f32_e32 v12, v12, v23
	v_mul_f32_e32 v11, 0xbfb8aa3b, v11
	v_fma_f32 v23, -v25, v26, 1.0
	s_waitcnt vmcnt(0)
	v_lshlrev_b32_e32 v27, 16, v19
	v_fmac_f32_e32 v26, v23, v26
	v_div_scale_f32 v23, vcc, 1.0, v13, 1.0
	v_exp_f32_e32 v11, v11
	v_mul_f32_e32 v12, v12, v27
	v_mul_f32_e32 v27, v23, v26
	v_fma_f32 v28, -v25, v27, v23
	v_fmac_f32_e32 v27, v28, v26
	v_fma_f32 v23, -v25, v27, v23
	v_add_f32_e32 v11, 1.0, v11
	v_div_fmas_f32 v23, v23, v26, v27
	v_div_scale_f32 v26, s[4:5], v11, v11, 1.0
	v_rcp_f32_e32 v27, v26
	v_div_fixup_f32 v13, v23, v13, 1.0
	v_mul_f32_e32 v23, 0x3fb8aa3b, v24
	v_exp_f32_e32 v25, v23
	v_fma_f32 v23, -v26, v27, 1.0
	v_fmac_f32_e32 v27, v23, v27
	v_div_scale_f32 v23, vcc, 1.0, v11, 1.0
	v_add_f32_e32 v10, v6, v10
	v_mul_f32_e32 v24, v23, v27
	v_mul_f32_e32 v10, 0xbfb8aa3b, v10
	v_fma_f32 v28, -v26, v24, v23
	v_exp_f32_e32 v10, v10
	v_fmac_f32_e32 v24, v28, v27
	v_fma_f32 v23, -v26, v24, v23
	v_div_fmas_f32 v23, v23, v27, v24
	v_div_fixup_f32 v11, v23, v11, 1.0
	v_add_f32_e32 v10, 1.0, v10
	v_and_b32_e32 v23, 0xffff0000, v18
	v_mul_f32_e32 v11, v11, v22
	v_div_scale_f32 v22, s[4:5], v10, v10, 1.0
	v_mul_f32_e32 v11, v11, v23
	v_rcp_f32_e32 v23, v22
	v_mul_f32_e32 v16, 0x3fb8aa3b, v16
	v_exp_f32_e32 v24, v16
	v_lshlrev_b32_e32 v16, 16, v18
	v_fma_f32 v18, -v22, v23, 1.0
	v_fmac_f32_e32 v23, v18, v23
	v_div_scale_f32 v18, vcc, 1.0, v10, 1.0
	v_mul_f32_e32 v26, v18, v23
	v_fma_f32 v27, -v22, v26, v18
	v_fmac_f32_e32 v26, v27, v23
	v_fma_f32 v18, -v22, v26, v18
	v_div_fmas_f32 v18, v18, v23, v26
	v_div_fixup_f32 v10, v18, v10, 1.0
	v_mul_f32_e32 v10, v10, v14
	v_mul_f32_e32 v14, 0x3fb8aa3b, v15
	v_mul_f32_e32 v0, 0x3fb8aa3b, v0
	v_exp_f32_e32 v23, v14
	v_exp_f32_e32 v22, v0
	v_and_b32_e32 v14, 0xffff0000, v19
	v_mul_f32_e32 v0, v13, v17
	v_mul_f32_e32 v13, v0, v14
	v_lshlrev_b64 v[14:15], 2, v[20:21]
	v_mul_f32_e32 v10, v10, v16
	v_lshl_add_u64 v[16:17], v[142:143], 0, v[14:15]
	v_lshl_add_u64 v[14:15], v[144:145], 0, v[14:15]
	global_store_dwordx4 v[16:17], v[22:25], off
	global_store_dwordx4 v[14:15], v[10:13], off

.LBB0_430:
	v_add_u32_e32 v0, s49, v139
	v_ashrrev_i32_e32 v10, 5, v0
	v_add_u32_e32 v20, s48, v10
	s_movk_i32 s4, 0x4080
	v_cmp_gt_i32_e32 vcc, s4, v20
	s_and_saveexec_b64 s[10:11], vcc
	s_cbranch_execz .LBB0_456
	v_ashrrev_i32_e32 v21, 31, v20
	v_lshlrev_b64 v[12:13], 10, v[20:21]
	v_lshl_add_u64 v[12:13], v[140:141], 0, v[12:13]
	global_load_dwordx2 v[18:19], v[12:13], off
	v_mad_u64_u32 v[10:11], s[4:5], v10, s33, v[138:139]
	ds_read_b128 v[14:17], v10
	ds_read_b128 v[10:13], v10 offset:512
	s_movk_i32 s4, 0x3fff
	v_cmp_lt_i32_e32 vcc, s4, v20
	v_and_b32_e32 v22, 0xfff, v20
	s_waitcnt vmcnt(2) lgkmcnt(1)
	v_add_f32_e32 v14, v2, v14
	v_mul_f32_e32 v14, 0xbfb8aa3b, v14
	v_exp_f32_e32 v14, v14
	s_nop 0
	v_add_f32_e32 v14, 1.0, v14
	v_cmp_ne_u32_e64 s[4:5], 0, v22
	s_or_b64 s[24:25], vcc, s[4:5]
	v_mov_b32_e32 v22, 1.0
	v_rcp_f32_e32 v14, v14
	s_nop 0
	v_mul_f32_e32 v14, 0xc1000000, v14
	v_mul_f32_e32 v14, v146, v14
	s_and_saveexec_b64 s[26:27], s[24:25]
	s_cbranch_execz .LBB0_437
	v_add_f32_e32 v23, v14, v14
	s_mov_b32 s4, 0xbdcccccd
	v_cmp_nlt_f32_e32 vcc, s4, v23
	s_and_saveexec_b64 s[4:5], vcc
	s_xor_b64 s[4:5], exec, s[4:5]
	v_mul_f32_e32 v22, 0x3fb8aa3b, v23
	v_exp_f32_e32 v22, v22
	s_nop 0
	v_sub_f32_e32 v22, 1.0, v22
	s_andn2_saveexec_b64 s[4:5], s[4:5]
	v_fmamk_f32 v22, v23, 0x3d2aaaab, v171
	v_fma_f32 v22, v23, v22, 0.5
	v_fma_f32 v22, v23, v22, 1.0
	v_mul_f32_e64 v22, v23, -v22
	s_or_b64 exec, exec, s[4:5]
	s_mov_b32 s4, 0xf800000
	v_mul_f32_e32 v23, 0x4f800000, v22
	v_cmp_gt_f32_e32 vcc, s4, v22
	s_nop 1
	v_cndmask_b32_e32 v22, v22, v23, vcc
	v_sqrt_f32_e32 v23, v22
	s_nop 0
	v_add_u32_e32 v24, -1, v23
	v_fma_f32 v26, -v24, v23, v22
	v_add_u32_e32 v25, 1, v23
	v_cmp_ge_f32_e64 s[4:5], 0, v26
	s_nop 1
	v_cndmask_b32_e64 v24, v23, v24, s[4:5]
	v_fma_f32 v23, -v25, v23, v22
	v_cmp_lt_f32_e64 s[4:5], 0, v23
	s_nop 1
	v_cndmask_b32_e64 v23, v24, v25, s[4:5]
	v_mul_f32_e32 v24, 0x37800000, v23
	v_cndmask_b32_e32 v23, v23, v24, vcc
	v_cmp_class_f32_e32 vcc, v22, v200
	s_nop 1
	v_cndmask_b32_e32 v22, v23, v22, vcc
.LBB0_437:
	s_or_b64 exec, exec, s[26:27]
	v_add_f32_e32 v15, v3, v15
	v_mul_f32_e32 v15, 0xbfb8aa3b, v15
	v_exp_f32_e32 v15, v15
	v_lshlrev_b64 v[20:21], 9, v[20:21]
	v_mov_b32_e32 v23, 1.0
	v_add_f32_e32 v15, 1.0, v15
	v_rcp_f32_e32 v15, v15
	s_nop 0
	v_mul_f32_e32 v15, 0xc1000000, v15
	v_mul_f32_e32 v15, v147, v15
	s_and_saveexec_b64 s[26:27], s[24:25]
	s_cbranch_execz .LBB0_443
	v_add_f32_e32 v24, v15, v15
	s_mov_b32 s4, 0xbdcccccd
	v_cmp_nlt_f32_e32 vcc, s4, v24
	s_and_saveexec_b64 s[4:5], vcc
	s_xor_b64 s[4:5], exec, s[4:5]
	v_mul_f32_e32 v23, 0x3fb8aa3b, v24
	v_exp_f32_e32 v23, v23
	s_nop 0
	v_sub_f32_e32 v23, 1.0, v23
	s_andn2_saveexec_b64 s[4:5], s[4:5]
	v_fmamk_f32 v23, v24, 0x3d2aaaab, v171
	v_fma_f32 v23, v24, v23, 0.5
	v_fma_f32 v23, v24, v23, 1.0
	v_mul_f32_e64 v23, v24, -v23
	s_or_b64 exec, exec, s[4:5]
	s_mov_b32 s4, 0xf800000
	v_mul_f32_e32 v24, 0x4f800000, v23
	v_cmp_gt_f32_e32 vcc, s4, v23
	s_nop 1
	v_cndmask_b32_e32 v23, v23, v24, vcc
	v_sqrt_f32_e32 v24, v23
	s_nop 0
	v_add_u32_e32 v25, -1, v24
	v_fma_f32 v27, -v25, v24, v23
	v_add_u32_e32 v26, 1, v24
	v_cmp_ge_f32_e64 s[4:5], 0, v27
	s_nop 1
	v_cndmask_b32_e64 v25, v24, v25, s[4:5]
	v_fma_f32 v24, -v26, v24, v23
	v_cmp_lt_f32_e64 s[4:5], 0, v24
	s_nop 1
	v_cndmask_b32_e64 v24, v25, v26, s[4:5]
	v_mul_f32_e32 v25, 0x37800000, v24
	v_cndmask_b32_e32 v24, v24, v25, vcc
	v_cmp_class_f32_e32 vcc, v23, v200
	s_nop 1
	v_cndmask_b32_e32 v23, v24, v23, vcc
.LBB0_443:
	s_or_b64 exec, exec, s[26:27]
	v_add_f32_e32 v16, v4, v16
	v_mul_f32_e32 v16, 0xbfb8aa3b, v16
	v_exp_f32_e32 v16, v16
	v_mov_b32_e32 v24, 1.0
	v_add_f32_e32 v16, 1.0, v16
	v_rcp_f32_e32 v16, v16
	s_nop 0
	v_mul_f32_e32 v16, 0xc1000000, v16
	v_mul_f32_e32 v16, v148, v16
	s_and_saveexec_b64 s[26:27], s[24:25]
	s_cbranch_execz .LBB0_449
	v_add_f32_e32 v25, v16, v16
	s_mov_b32 s4, 0xbdcccccd
	v_cmp_nlt_f32_e32 vcc, s4, v25
	s_and_saveexec_b64 s[4:5], vcc
	s_xor_b64 s[4:5], exec, s[4:5]
	v_mul_f32_e32 v24, 0x3fb8aa3b, v25
	v_exp_f32_e32 v24, v24
	s_nop 0
	v_sub_f32_e32 v24, 1.0, v24
	s_andn2_saveexec_b64 s[4:5], s[4:5]
	v_fmamk_f32 v24, v25, 0x3d2aaaab, v171
	v_fma_f32 v24, v25, v24, 0.5
	v_fma_f32 v24, v25, v24, 1.0
	v_mul_f32_e64 v24, v25, -v24
	s_or_b64 exec, exec, s[4:5]
	s_mov_b32 s4, 0xf800000
	v_mul_f32_e32 v25, 0x4f800000, v24
	v_cmp_gt_f32_e32 vcc, s4, v24
	s_nop 1
	v_cndmask_b32_e32 v24, v24, v25, vcc
	v_sqrt_f32_e32 v25, v24
	s_nop 0
	v_add_u32_e32 v26, -1, v25
	v_fma_f32 v28, -v26, v25, v24
	v_add_u32_e32 v27, 1, v25
	v_cmp_ge_f32_e64 s[4:5], 0, v28
	s_nop 1
	v_cndmask_b32_e64 v26, v25, v26, s[4:5]
	v_fma_f32 v25, -v27, v25, v24
	v_cmp_lt_f32_e64 s[4:5], 0, v25
	s_nop 1
	v_cndmask_b32_e64 v25, v26, v27, s[4:5]
	v_mul_f32_e32 v26, 0x37800000, v25
	v_cndmask_b32_e32 v25, v25, v26, vcc
	v_cmp_class_f32_e32 vcc, v24, v200
	s_nop 1
	v_cndmask_b32_e32 v24, v25, v24, vcc
.LBB0_449:
	s_or_b64 exec, exec, s[26:27]
	v_add_f32_e32 v17, v5, v17
	v_mul_f32_e32 v17, 0xbfb8aa3b, v17
	v_exp_f32_e32 v17, v17
	s_nop 0
	v_add_f32_e32 v25, 1.0, v17
	v_mov_b32_e32 v17, 1.0
	v_rcp_f32_e32 v25, v25
	s_nop 0
	v_mul_f32_e32 v25, 0xc1000000, v25
	v_mul_f32_e32 v25, v149, v25
	s_and_saveexec_b64 s[26:27], s[24:25]
	s_cbranch_execz .LBB0_455
	v_add_f32_e32 v26, v25, v25
	s_mov_b32 s4, 0xbdcccccd
	v_cmp_nlt_f32_e32 vcc, s4, v26
	s_and_saveexec_b64 s[4:5], vcc
	s_xor_b64 s[4:5], exec, s[4:5]
	v_mul_f32_e32 v17, 0x3fb8aa3b, v26
	v_exp_f32_e32 v17, v17
	s_nop 0
	v_sub_f32_e32 v17, 1.0, v17
	s_andn2_saveexec_b64 s[4:5], s[4:5]
	v_fmamk_f32 v17, v26, 0x3d2aaaab, v171
	v_fma_f32 v17, v26, v17, 0.5
	v_fma_f32 v17, v26, v17, 1.0
	v_mul_f32_e64 v17, v26, -v17
	s_or_b64 exec, exec, s[4:5]
	s_mov_b32 s4, 0xf800000
	v_mul_f32_e32 v26, 0x4f800000, v17
	v_cmp_gt_f32_e32 vcc, s4, v17
	s_nop 1
	v_cndmask_b32_e32 v17, v17, v26, vcc
	v_sqrt_f32_e32 v26, v17
	s_nop 0
	v_add_u32_e32 v27, -1, v26
	v_fma_f32 v29, -v27, v26, v17
	v_add_u32_e32 v28, 1, v26
	v_cmp_ge_f32_e64 s[4:5], 0, v29
	s_nop 1
	v_cndmask_b32_e64 v27, v26, v27, s[4:5]
	v_fma_f32 v26, -v28, v26, v17
	v_cmp_lt_f32_e64 s[4:5], 0, v26
	s_nop 1
	v_cndmask_b32_e64 v26, v27, v28, s[4:5]
	v_mul_f32_e32 v27, 0x37800000, v26
	v_cndmask_b32_e32 v26, v26, v27, vcc
	v_cmp_class_f32_e32 vcc, v17, v200
	s_nop 1
	v_cndmask_b32_e32 v17, v26, v17, vcc
.LBB0_455:
	s_or_b64 exec, exec, s[26:27]
	s_waitcnt vmcnt(1) lgkmcnt(0)
	v_add_f32_e32 v12, v8, v12
	v_mul_f32_e32 v12, 0xbfb8aa3b, v12
	v_exp_f32_e32 v12, v12
	v_add_f32_e32 v13, v9, v13
	v_mul_f32_e32 v13, 0xbfb8aa3b, v13
	v_exp_f32_e32 v13, v13
	v_add_f32_e32 v12, 1.0, v12
	v_add_f32_e32 v13, 1.0, v13
	v_rcp_f32_e32 v12, v12
	s_nop 0
	v_div_scale_f32 v26, s[4:5], v13, v13, 1.0
	v_rcp_f32_e32 v27, v26
	v_add_f32_e32 v11, v7, v11
	v_mul_f32_e32 v11, 0xbfb8aa3b, v11
	v_mul_f32_e32 v12, v12, v24
	v_fma_f32 v24, -v26, v27, 1.0
	v_exp_f32_e32 v11, v11
	s_waitcnt vmcnt(0)
	v_lshlrev_b32_e32 v28, 16, v19
	v_fmac_f32_e32 v27, v24, v27
	v_div_scale_f32 v24, vcc, 1.0, v13, 1.0
	v_mul_f32_e32 v12, v12, v28
	v_mul_f32_e32 v28, v24, v27
	v_fma_f32 v29, -v26, v28, v24
	v_fmac_f32_e32 v28, v29, v27
	v_add_f32_e32 v11, 1.0, v11
	v_fma_f32 v24, -v26, v28, v24
	v_div_scale_f32 v26, s[4:5], v11, v11, 1.0
	v_div_fmas_f32 v24, v24, v27, v28
	v_rcp_f32_e32 v27, v26
	v_div_fixup_f32 v13, v24, v13, 1.0
	v_mul_f32_e32 v24, 0x3fb8aa3b, v25
	v_exp_f32_e32 v25, v24
	v_fma_f32 v24, -v26, v27, 1.0
	v_fmac_f32_e32 v27, v24, v27
	v_div_scale_f32 v24, vcc, 1.0, v11, 1.0
	v_add_f32_e32 v10, v6, v10
	v_mul_f32_e32 v28, v24, v27
	v_mul_f32_e32 v10, 0xbfb8aa3b, v10
	v_fma_f32 v29, -v26, v28, v24
	v_exp_f32_e32 v10, v10
	v_fmac_f32_e32 v28, v29, v27
	v_fma_f32 v24, -v26, v28, v24
	v_div_fmas_f32 v24, v24, v27, v28
	v_div_fixup_f32 v11, v24, v11, 1.0
	v_add_f32_e32 v10, 1.0, v10
	v_mul_f32_e32 v11, v11, v23
	v_div_scale_f32 v23, s[4:5], v10, v10, 1.0
	v_rcp_f32_e32 v26, v23
	v_and_b32_e32 v24, 0xffff0000, v18
	v_mul_f32_e32 v16, 0x3fb8aa3b, v16
	v_mul_f32_e32 v11, v11, v24
	v_exp_f32_e32 v24, v16
	v_lshlrev_b32_e32 v16, 16, v18
	v_fma_f32 v18, -v23, v26, 1.0
	v_fmac_f32_e32 v26, v18, v26
	v_div_scale_f32 v18, vcc, 1.0, v10, 1.0
	v_mul_f32_e32 v27, v18, v26
	v_fma_f32 v28, -v23, v27, v18
	v_fmac_f32_e32 v27, v28, v26
	v_fma_f32 v18, -v23, v27, v18
	v_div_fmas_f32 v18, v18, v26, v27
	v_div_fixup_f32 v10, v18, v10, 1.0
	v_mul_f32_e32 v15, 0x3fb8aa3b, v15
	v_mul_f32_e32 v14, 0x3fb8aa3b, v14
	v_mul_f32_e32 v10, v10, v22
	v_exp_f32_e32 v23, v15
	v_exp_f32_e32 v22, v14
	v_and_b32_e32 v15, 0xffff0000, v19
	v_mul_f32_e32 v13, v13, v17
	v_mul_f32_e32 v13, v13, v15
	v_lshlrev_b64 v[14:15], 2, v[20:21]
	v_mul_f32_e32 v10, v10, v16
	v_lshl_add_u64 v[16:17], v[142:143], 0, v[14:15]
	v_lshl_add_u64 v[14:15], v[144:145], 0, v[14:15]
	global_store_dwordx4 v[16:17], v[22:25], off
	global_store_dwordx4 v[14:15], v[10:13], off
.LBB0_456:
	s_or_b64 exec, exec, s[10:11]
	v_add_u32_e32 v0, 0x200, v0
	v_ashrrev_i32_e32 v0, 5, v0
	v_add_u32_e32 v20, s48, v0
	s_movk_i32 s4, 0x4080
	v_cmp_gt_i32_e32 vcc, s4, v20
	s_and_saveexec_b64 s[10:11], vcc
	s_cbranch_execz .LBB0_429
	v_ashrrev_i32_e32 v21, 31, v20
	v_lshlrev_b64 v[10:11], 10, v[20:21]
	v_lshl_add_u64 v[10:11], v[140:141], 0, v[10:11]
	global_load_dwordx2 v[18:19], v[10:11], off
	v_mad_u64_u32 v[10:11], s[4:5], v0, s33, v[138:139]
	ds_read_b128 v[14:17], v10
	ds_read_b128 v[10:13], v10 offset:512
	s_movk_i32 s4, 0x3fff
	v_cmp_lt_i32_e32 vcc, s4, v20
	s_waitcnt vmcnt(2) lgkmcnt(1)
	v_add_f32_e32 v0, v2, v14
	v_mul_f32_e32 v0, 0xbfb8aa3b, v0
	v_exp_f32_e32 v0, v0
	v_and_b32_e32 v14, 0xfff, v20
	v_add_f32_e32 v0, 1.0, v0
	v_cmp_ne_u32_e64 s[4:5], 0, v14
	s_or_b64 s[24:25], vcc, s[4:5]
	v_mov_b32_e32 v14, 1.0
	v_rcp_f32_e32 v0, v0
	s_nop 0
	v_mul_f32_e32 v0, 0xc1000000, v0
	v_mul_f32_e32 v0, v146, v0
	s_and_saveexec_b64 s[26:27], s[24:25]
	s_cbranch_execz .LBB0_463
	v_add_f32_e32 v22, v0, v0
	s_mov_b32 s4, 0xbdcccccd
	v_cmp_nlt_f32_e32 vcc, s4, v22
	s_and_saveexec_b64 s[4:5], vcc
	s_xor_b64 s[4:5], exec, s[4:5]
	v_mul_f32_e32 v14, 0x3fb8aa3b, v22
	v_exp_f32_e32 v14, v14
	s_nop 0
	v_sub_f32_e32 v14, 1.0, v14
	s_andn2_saveexec_b64 s[4:5], s[4:5]
	v_fmamk_f32 v14, v22, 0x3d2aaaab, v171
	v_fma_f32 v14, v22, v14, 0.5
	v_fma_f32 v14, v22, v14, 1.0
	v_mul_f32_e64 v14, v22, -v14
	s_or_b64 exec, exec, s[4:5]
	s_mov_b32 s4, 0xf800000
	v_mul_f32_e32 v22, 0x4f800000, v14
	v_cmp_gt_f32_e32 vcc, s4, v14
	s_nop 1
	v_cndmask_b32_e32 v14, v14, v22, vcc
	v_sqrt_f32_e32 v22, v14
	s_nop 0
	v_add_u32_e32 v23, -1, v22
	v_fma_f32 v25, -v23, v22, v14
	v_add_u32_e32 v24, 1, v22
	v_cmp_ge_f32_e64 s[4:5], 0, v25
	s_nop 1
	v_cndmask_b32_e64 v23, v22, v23, s[4:5]
	v_fma_f32 v22, -v24, v22, v14
	v_cmp_lt_f32_e64 s[4:5], 0, v22
	s_nop 1
	v_cndmask_b32_e64 v22, v23, v24, s[4:5]
	v_mul_f32_e32 v23, 0x37800000, v22
	v_cndmask_b32_e32 v22, v22, v23, vcc
	v_cmp_class_f32_e32 vcc, v14, v200
	s_nop 1
	v_cndmask_b32_e32 v14, v22, v14, vcc
.LBB0_463:
	s_or_b64 exec, exec, s[26:27]
	v_add_f32_e32 v15, v3, v15
	v_mul_f32_e32 v15, 0xbfb8aa3b, v15
	v_exp_f32_e32 v15, v15
	v_lshlrev_b64 v[20:21], 9, v[20:21]
	v_mov_b32_e32 v22, 1.0
	v_add_f32_e32 v15, 1.0, v15
	v_rcp_f32_e32 v15, v15
	s_nop 0
	v_mul_f32_e32 v15, 0xc1000000, v15
	v_mul_f32_e32 v15, v147, v15
	s_and_saveexec_b64 s[26:27], s[24:25]
	s_cbranch_execz .LBB0_469
	v_add_f32_e32 v23, v15, v15
	s_mov_b32 s4, 0xbdcccccd
	v_cmp_nlt_f32_e32 vcc, s4, v23
	s_and_saveexec_b64 s[4:5], vcc
	s_xor_b64 s[4:5], exec, s[4:5]
	v_mul_f32_e32 v22, 0x3fb8aa3b, v23
	v_exp_f32_e32 v22, v22
	s_nop 0
	v_sub_f32_e32 v22, 1.0, v22
	s_andn2_saveexec_b64 s[4:5], s[4:5]
	v_fmamk_f32 v22, v23, 0x3d2aaaab, v171
	v_fma_f32 v22, v23, v22, 0.5
	v_fma_f32 v22, v23, v22, 1.0
	v_mul_f32_e64 v22, v23, -v22
	s_or_b64 exec, exec, s[4:5]
	s_mov_b32 s4, 0xf800000
	v_mul_f32_e32 v23, 0x4f800000, v22
	v_cmp_gt_f32_e32 vcc, s4, v22
	s_nop 1
	v_cndmask_b32_e32 v22, v22, v23, vcc
	v_sqrt_f32_e32 v23, v22
	s_nop 0
	v_add_u32_e32 v24, -1, v23
	v_fma_f32 v26, -v24, v23, v22
	v_add_u32_e32 v25, 1, v23
	v_cmp_ge_f32_e64 s[4:5], 0, v26
	s_nop 1
	v_cndmask_b32_e64 v24, v23, v24, s[4:5]
	v_fma_f32 v23, -v25, v23, v22
	v_cmp_lt_f32_e64 s[4:5], 0, v23
	s_nop 1
	v_cndmask_b32_e64 v23, v24, v25, s[4:5]
	v_mul_f32_e32 v24, 0x37800000, v23
	v_cndmask_b32_e32 v23, v23, v24, vcc
	v_cmp_class_f32_e32 vcc, v22, v200
	s_nop 1
	v_cndmask_b32_e32 v22, v23, v22, vcc
.LBB0_469:
	s_or_b64 exec, exec, s[26:27]
	v_add_f32_e32 v16, v4, v16
	v_mul_f32_e32 v16, 0xbfb8aa3b, v16
	v_exp_f32_e32 v16, v16
	v_mov_b32_e32 v23, 1.0
	v_add_f32_e32 v16, 1.0, v16
	v_rcp_f32_e32 v16, v16
	s_nop 0
	v_mul_f32_e32 v16, 0xc1000000, v16
	v_mul_f32_e32 v16, v148, v16
	s_and_saveexec_b64 s[26:27], s[24:25]
	s_cbranch_execz .LBB0_475
	v_add_f32_e32 v24, v16, v16
	s_mov_b32 s4, 0xbdcccccd
	v_cmp_nlt_f32_e32 vcc, s4, v24
	s_and_saveexec_b64 s[4:5], vcc
	s_xor_b64 s[4:5], exec, s[4:5]
	v_mul_f32_e32 v23, 0x3fb8aa3b, v24
	v_exp_f32_e32 v23, v23
	s_nop 0
	v_sub_f32_e32 v23, 1.0, v23
	s_andn2_saveexec_b64 s[4:5], s[4:5]
	v_fmamk_f32 v23, v24, 0x3d2aaaab, v171
	v_fma_f32 v23, v24, v23, 0.5
	v_fma_f32 v23, v24, v23, 1.0
	v_mul_f32_e64 v23, v24, -v23
	s_or_b64 exec, exec, s[4:5]
	s_mov_b32 s4, 0xf800000
	v_mul_f32_e32 v24, 0x4f800000, v23
	v_cmp_gt_f32_e32 vcc, s4, v23
	s_nop 1
	v_cndmask_b32_e32 v23, v23, v24, vcc
	v_sqrt_f32_e32 v24, v23
	s_nop 0
	v_add_u32_e32 v25, -1, v24
	v_fma_f32 v27, -v25, v24, v23
	v_add_u32_e32 v26, 1, v24
	v_cmp_ge_f32_e64 s[4:5], 0, v27
	s_nop 1
	v_cndmask_b32_e64 v25, v24, v25, s[4:5]
	v_fma_f32 v24, -v26, v24, v23
	v_cmp_lt_f32_e64 s[4:5], 0, v24
	s_nop 1
	v_cndmask_b32_e64 v24, v25, v26, s[4:5]
	v_mul_f32_e32 v25, 0x37800000, v24
	v_cndmask_b32_e32 v24, v24, v25, vcc
	v_cmp_class_f32_e32 vcc, v23, v200
	s_nop 1
	v_cndmask_b32_e32 v23, v24, v23, vcc
.LBB0_475:
	s_or_b64 exec, exec, s[26:27]
	v_add_f32_e32 v17, v5, v17
	v_mul_f32_e32 v17, 0xbfb8aa3b, v17
	v_exp_f32_e32 v17, v17
	s_nop 0
	v_add_f32_e32 v24, 1.0, v17
	v_mov_b32_e32 v17, 1.0
	v_rcp_f32_e32 v24, v24
	s_nop 0
	v_mul_f32_e32 v24, 0xc1000000, v24
	v_mul_f32_e32 v24, v149, v24
	s_and_saveexec_b64 s[26:27], s[24:25]
	s_cbranch_execz .LBB0_428
	v_add_f32_e32 v25, v24, v24
	s_mov_b32 s4, 0xbdcccccd
	v_cmp_nlt_f32_e32 vcc, s4, v25
	s_and_saveexec_b64 s[4:5], vcc
	s_xor_b64 s[4:5], exec, s[4:5]
	v_mul_f32_e32 v17, 0x3fb8aa3b, v25
	v_exp_f32_e32 v17, v17
	s_nop 0
	v_sub_f32_e32 v17, 1.0, v17
	s_andn2_saveexec_b64 s[4:5], s[4:5]
	s_cbranch_execz .LBB0_427
	v_fmamk_f32 v17, v25, 0x3d2aaaab, v171
	v_fma_f32 v17, v25, v17, 0.5
	v_fma_f32 v17, v25, v17, 1.0
	v_mul_f32_e64 v17, v25, -v17
	s_branch .LBB0_427
